# attention output tails: subln gamma loads hoisted (no per-store vmcnt(0)), dwordx2 stores paired into dwordx4 via v_permlane32_swap (diff and MoBA outputs)
# baseline (speedup 1.0000x reference)
; __global__ void __launch_bounds__(512, 2) mega_fwd(Args a) {
;     ...
;                 float ss = 0.f;
; #pragma unroll
;                 for (int d = 0; d < 4; ++d) {
; #pragma unroll
;                     for (int g4 = 0; g4 < 4; ++g4) { const f32x4 s0 = stash[d * 4 + g4];
; #pragma unroll
;                         for (int j = 0; j < 4; ++j) { const float v = s0[j] - lam * o[d][4 * g4 + j]; o[d][4 * g4 + j] = v; ss += v * v; } }
;                     __builtin_amdgcn_sched_barrier(0); }
;                 ss += __shfl_xor(ss, 32);
;                 const float rinv = rsqrtf(ss * (1.0f / 128.0f) + RMS_EPS) * 0.8f;
;                 bf16_t* op = OA + row * 1024 + h * 128;
; #pragma unroll
;                 for (int d = 0; d < 4; ++d)
; #pragma unroll
;                     for (int g4 = 0; g4 < 4; ++g4) { const int dd = 32 * d + 8 * g4 + 4 * hi; const f32x4 gs = *(const f32x4*)(a.in[10] + dd);
.LBB0_554:
	global_load_dwordx4 v[30:33], v[132:133], off offset:48
	global_load_dwordx4 v[46:49], v[132:133], off offset:32
	global_load_dwordx4 v[78:81], v[132:133], off offset:16
	global_load_dwordx4 v[82:85], v[132:133], off
	global_load_dwordx4 v[86:89], v[132:133], off offset:112
	global_load_dwordx4 v[90:93], v[132:133], off offset:96
	global_load_dwordx4 v[94:97], v[132:133], off offset:80
	global_load_dwordx4 v[98:101], v[132:133], off offset:64
	global_load_dwordx4 v[102:105], v[132:133], off offset:176
	global_load_dwordx4 v[106:109], v[132:133], off offset:160
	global_load_dwordx4 v[110:113], v[132:133], off offset:144
	global_load_dwordx4 v[114:117], v[132:133], off offset:128
	global_load_dwordx4 v[14:17], v[132:133], off offset:240
	global_load_dwordx4 v[118:121], v[132:133], off offset:224
	global_load_dwordx4 v[122:125], v[132:133], off offset:208
	s_nop 0
	global_load_dwordx4 v[132:135], v[132:133], off offset:192
	s_waitcnt vmcnt(3)
	v_pk_fma_f32 v[14:15], v[148:149], v[10:11], v[14:15] neg_lo:[1,0,0] neg_hi:[1,0,0]
	v_pk_fma_f32 v[10:11], v[148:149], v[12:13], v[16:17] neg_lo:[1,0,0] neg_hi:[1,0,0]
	v_pk_mul_f32 v[140:141], v[14:15], v[14:15]
	v_pk_mul_f32 v[142:143], v[10:11], v[10:11]
	v_pk_fma_f32 v[74:75], v[148:149], v[74:75], v[82:83] neg_lo:[1,0,0] neg_hi:[1,0,0]
	v_pk_fma_f32 v[76:77], v[148:149], v[76:77], v[84:85] neg_lo:[1,0,0] neg_hi:[1,0,0]
	v_pk_mul_f32 v[82:83], v[74:75], v[74:75]
	global_load_dwordx4 v[136:139], v126, s[20:21]
	v_pk_mul_f32 v[84:85], v[76:77], v[76:77]
	v_add_f32_e32 v1, v82, v83
	v_pk_fma_f32 v[70:71], v[148:149], v[70:71], v[78:79] neg_lo:[1,0,0] neg_hi:[1,0,0]
	v_add_f32_e32 v1, v1, v84
	v_pk_mul_f32 v[78:79], v[70:71], v[70:71]
	v_add_f32_e32 v1, v1, v85
	v_pk_fma_f32 v[72:73], v[148:149], v[72:73], v[80:81] neg_lo:[1,0,0] neg_hi:[1,0,0]
	v_add_f32_e32 v1, v1, v78
	v_pk_mul_f32 v[80:81], v[72:73], v[72:73]
	v_add_f32_e32 v1, v1, v79
	v_pk_fma_f32 v[66:67], v[148:149], v[66:67], v[46:47] neg_lo:[1,0,0] neg_hi:[1,0,0]
	v_add_f32_e32 v1, v1, v80
	v_pk_mul_f32 v[146:147], v[66:67], v[66:67]
	v_add_f32_e32 v1, v1, v81
	v_pk_fma_f32 v[68:69], v[148:149], v[68:69], v[48:49] neg_lo:[1,0,0] neg_hi:[1,0,0]
	v_add_f32_e32 v1, v1, v146
	v_pk_mul_f32 v[144:145], v[68:69], v[68:69]
	v_add_f32_e32 v1, v1, v147
	v_pk_fma_f32 v[62:63], v[148:149], v[62:63], v[30:31] neg_lo:[1,0,0] neg_hi:[1,0,0]
	v_add_f32_e32 v1, v1, v144
	v_pk_mul_f32 v[152:153], v[62:63], v[62:63]
	v_add_f32_e32 v1, v1, v145
	v_pk_fma_f32 v[64:65], v[148:149], v[64:65], v[32:33] neg_lo:[1,0,0] neg_hi:[1,0,0]
	v_add_f32_e32 v1, v1, v152
	v_pk_mul_f32 v[150:151], v[64:65], v[64:65]
	v_add_f32_e32 v1, v1, v153
	v_pk_fma_f32 v[58:59], v[148:149], v[58:59], v[98:99] neg_lo:[1,0,0] neg_hi:[1,0,0]
	v_add_f32_e32 v1, v1, v150
	v_pk_mul_f32 v[98:99], v[58:59], v[58:59]
	v_add_f32_e32 v1, v1, v151
	v_pk_fma_f32 v[60:61], v[148:149], v[60:61], v[100:101] neg_lo:[1,0,0] neg_hi:[1,0,0]
	v_add_f32_e32 v1, v1, v98
	v_pk_mul_f32 v[100:101], v[60:61], v[60:61]
	v_add_f32_e32 v1, v1, v99
	v_pk_fma_f32 v[54:55], v[148:149], v[54:55], v[94:95] neg_lo:[1,0,0] neg_hi:[1,0,0]
	v_add_f32_e32 v1, v1, v100
	v_pk_mul_f32 v[94:95], v[54:55], v[54:55]
	v_add_f32_e32 v1, v1, v101
	v_pk_fma_f32 v[56:57], v[148:149], v[56:57], v[96:97] neg_lo:[1,0,0] neg_hi:[1,0,0]
	v_add_f32_e32 v1, v1, v94
	v_pk_mul_f32 v[96:97], v[56:57], v[56:57]
	v_add_f32_e32 v1, v1, v95
	v_pk_fma_f32 v[48:49], v[148:149], v[50:51], v[90:91] neg_lo:[1,0,0] neg_hi:[1,0,0]
	v_add_f32_e32 v1, v1, v96
	v_pk_mul_f32 v[50:51], v[48:49], v[48:49]
	v_add_f32_e32 v1, v1, v97
	v_pk_fma_f32 v[46:47], v[148:149], v[52:53], v[92:93] neg_lo:[1,0,0] neg_hi:[1,0,0]
	v_add_f32_e32 v1, v1, v50
	v_pk_mul_f32 v[52:53], v[46:47], v[46:47]
	v_add_f32_e32 v1, v1, v51
	v_pk_fma_f32 v[42:43], v[148:149], v[42:43], v[86:87] neg_lo:[1,0,0] neg_hi:[1,0,0]
	v_add_f32_e32 v1, v1, v52
	v_pk_mul_f32 v[86:87], v[42:43], v[42:43]
	v_add_f32_e32 v1, v1, v53
	v_pk_fma_f32 v[44:45], v[148:149], v[44:45], v[88:89] neg_lo:[1,0,0] neg_hi:[1,0,0]
	v_add_f32_e32 v1, v1, v86
	v_pk_mul_f32 v[88:89], v[44:45], v[44:45]
	v_add_f32_e32 v1, v1, v87
	v_pk_fma_f32 v[38:39], v[148:149], v[38:39], v[114:115] neg_lo:[1,0,0] neg_hi:[1,0,0]
	v_add_f32_e32 v1, v1, v88
	v_pk_mul_f32 v[92:93], v[38:39], v[38:39]
	v_add_f32_e32 v1, v1, v89
	v_pk_fma_f32 v[40:41], v[148:149], v[40:41], v[116:117] neg_lo:[1,0,0] neg_hi:[1,0,0]
	v_add_f32_e32 v1, v1, v92
	v_pk_mul_f32 v[90:91], v[40:41], v[40:41]
	v_add_f32_e32 v1, v1, v93
	v_pk_fma_f32 v[32:33], v[148:149], v[34:35], v[110:111] neg_lo:[1,0,0] neg_hi:[1,0,0]
	v_add_f32_e32 v1, v1, v90
	v_pk_mul_f32 v[34:35], v[32:33], v[32:33]
	v_add_f32_e32 v1, v1, v91
	v_pk_fma_f32 v[30:31], v[148:149], v[36:37], v[112:113] neg_lo:[1,0,0] neg_hi:[1,0,0]
	v_add_f32_e32 v1, v1, v34
	v_pk_mul_f32 v[36:37], v[30:31], v[30:31]
	v_add_f32_e32 v1, v1, v35
	v_pk_fma_f32 v[26:27], v[148:149], v[26:27], v[106:107] neg_lo:[1,0,0] neg_hi:[1,0,0]
	v_add_f32_e32 v1, v1, v36
	v_pk_mul_f32 v[106:107], v[26:27], v[26:27]
	v_add_f32_e32 v1, v1, v37
	v_pk_fma_f32 v[28:29], v[148:149], v[28:29], v[108:109] neg_lo:[1,0,0] neg_hi:[1,0,0]
	v_add_f32_e32 v1, v1, v106
	v_pk_mul_f32 v[108:109], v[28:29], v[28:29]
	v_add_f32_e32 v1, v1, v107
	v_pk_fma_f32 v[22:23], v[148:149], v[22:23], v[102:103] neg_lo:[1,0,0] neg_hi:[1,0,0]
	v_add_f32_e32 v1, v1, v108
	v_pk_mul_f32 v[102:103], v[22:23], v[22:23]
	v_add_f32_e32 v1, v1, v109
	v_pk_fma_f32 v[24:25], v[148:149], v[24:25], v[104:105] neg_lo:[1,0,0] neg_hi:[1,0,0]
	v_add_f32_e32 v1, v1, v102
	v_pk_mul_f32 v[104:105], v[24:25], v[24:25]
	v_add_f32_e32 v1, v1, v103
	s_waitcnt vmcnt(1)
; __device__ __forceinline__ unsigned cvt_pk_bf16(float lo, float hi) { f32x2 v = {lo, hi}; bf16x2_t b = __builtin_convertvector(v, bf16x2_t); return __builtin_bit_cast(unsigned, b); }
; __global__ void __launch_bounds__(512, 2) mega_fwd(Args a) {
;     ...
;                 ss += __shfl_xor(ss, 32);
;                 const float rinv = rsqrtf(ss * (1.0f / 128.0f) + RMS_EPS) * 0.8f;
;                 bf16_t* op = OA + row * 1024 + h * 128;
; #pragma unroll
;                 for (int d = 0; d < 4; ++d)
; #pragma unroll
;                     for (int g4 = 0; g4 < 4; ++g4) { const int dd = 32 * d + 8 * g4 + 4 * hi; const f32x4 gs = *(const f32x4*)(a.in[10] + dd);
;                         u32x2 w; w.x = cvt_pk_bf16(o[d][4 * g4 + 0] * rinv * gs[0], o[d][4 * g4 + 1] * rinv * gs[1]); w.y = cvt_pk_bf16(o[d][4 * g4 + 2] * rinv * gs[2], o[d][4 * g4 + 3] * rinv * gs[3]);
;                         *(u32x2*)(op + dd) = w; }
	v_pk_fma_f32 v[16:17], v[148:149], v[18:19], v[132:133] neg_lo:[1,0,0] neg_hi:[1,0,0]
	v_add_f32_e32 v1, v1, v104
	v_pk_mul_f32 v[18:19], v[16:17], v[16:17]
	v_add_f32_e32 v1, v1, v105
	v_pk_fma_f32 v[12:13], v[148:149], v[20:21], v[134:135] neg_lo:[1,0,0] neg_hi:[1,0,0]
	v_add_f32_e32 v1, v1, v18
	v_pk_mul_f32 v[20:21], v[12:13], v[12:13]
	v_add_f32_e32 v1, v1, v19
	v_pk_fma_f32 v[6:7], v[148:149], v[6:7], v[122:123] neg_lo:[1,0,0] neg_hi:[1,0,0]
	v_add_f32_e32 v1, v1, v20
	v_pk_mul_f32 v[112:113], v[6:7], v[6:7]
	v_add_f32_e32 v1, v1, v21
	v_pk_fma_f32 v[8:9], v[148:149], v[8:9], v[124:125] neg_lo:[1,0,0] neg_hi:[1,0,0]
	v_add_f32_e32 v1, v1, v112
	v_pk_mul_f32 v[110:111], v[8:9], v[8:9]
	v_add_f32_e32 v1, v1, v113
	v_pk_fma_f32 v[2:3], v[148:149], v[2:3], v[118:119] neg_lo:[1,0,0] neg_hi:[1,0,0]
	v_add_f32_e32 v1, v1, v110
	v_pk_mul_f32 v[116:117], v[2:3], v[2:3]
	v_add_f32_e32 v1, v1, v111
	v_pk_fma_f32 v[4:5], v[148:149], v[4:5], v[120:121] neg_lo:[1,0,0] neg_hi:[1,0,0]
	v_add_f32_e32 v1, v1, v116
	v_pk_mul_f32 v[114:115], v[4:5], v[4:5]
	v_add_f32_e32 v1, v1, v117
	v_add_f32_e32 v1, v1, v114
	v_add_f32_e32 v1, v1, v115
	v_add_f32_e32 v1, v1, v140
	v_add_f32_e32 v1, v1, v141
	v_add_f32_e32 v1, v1, v142
	v_add_f32_e32 v1, v1, v143
	global_load_dwordx4 v[78:81], v126, s[20:21] offset:32
	global_load_dwordx4 v[82:85], v126, s[20:21] offset:64
	global_load_dwordx4 v[86:89], v126, s[20:21] offset:96
	global_load_dwordx4 v[90:93], v126, s[20:21] offset:128
	global_load_dwordx4 v[94:97], v126, s[20:21] offset:160
	global_load_dwordx4 v[98:101], v126, s[20:21] offset:192
	global_load_dwordx4 v[102:105], v126, s[20:21] offset:224
	global_load_dwordx4 v[106:109], v126, s[20:21] offset:256
	global_load_dwordx4 v[110:113], v126, s[20:21] offset:288
	global_load_dwordx4 v[114:117], v126, s[20:21] offset:320
	global_load_dwordx4 v[118:121], v126, s[20:21] offset:352
	global_load_dwordx4 v[122:125], v126, s[20:21] offset:384
	global_load_dwordx4 v[140:143], v126, s[20:21] offset:416
	global_load_dwordx4 v[144:147], v126, s[20:21] offset:448
	global_load_dwordx4 v[150:153], v126, s[20:21] offset:480
	ds_bpermute_b32 v20, v223, v1
	s_mov_b32 s0, 0x800000
	v_lshlrev_b64 v[18:19], 11, v[128:129]
	v_lshl_add_u64 v[18:19], s[38:39], 0, v[18:19]
	s_lshl_b32 s10, s14, 1
	s_waitcnt lgkmcnt(0)
	v_add_f32_e32 v1, v1, v20
	v_fmamk_f32 v1, v1, 0x3c000000, v210
	v_mul_f32_e32 v20, 0x4b800000, v1
	v_cmp_gt_f32_e32 vcc, s0, v1
	v_lshl_add_u64 v[18:19], v[18:19], 0, s[10:11]
	v_mov_b32_e32 v131, v0
	v_cndmask_b32_e32 v1, v1, v20, vcc
	v_rsq_f32_e32 v1, v1
	v_lshl_add_u64 v[18:19], v[18:19], 0, v[130:131]
	v_mul_f32_e32 v20, 0x45800000, v1
	v_cndmask_b32_e32 v1, v1, v20, vcc
	v_mul_f32_e32 v20, 0x3f4ccccd, v1
	v_mbcnt_lo_u32_b32 v132, -1, 0
	v_mbcnt_hi_u32_b32 v132, -1, v132
	v_lshrrev_b32_e32 v132, 5, v132
	v_lshlrev_b32_e32 v132, 3, v132
	v_mov_b32_e32 v133, 0
	v_lshl_add_u64 v[132:133], v[18:19], 0, v[132:133]
	s_waitcnt vmcnt(14)
	v_pk_mul_f32 v[74:75], v[20:21], v[74:75] op_sel_hi:[0,1]
	v_pk_mul_f32 v[76:77], v[20:21], v[76:77] op_sel_hi:[0,1]
	v_pk_mul_f32 v[70:71], v[20:21], v[70:71] op_sel_hi:[0,1]
	v_pk_mul_f32 v[72:73], v[20:21], v[72:73] op_sel_hi:[0,1]
	v_pk_mul_f32 v[136:137], v[136:137], v[74:75]
	v_pk_mul_f32 v[138:139], v[138:139], v[76:77]
	v_pk_mul_f32 v[78:79], v[78:79], v[70:71]
	v_pk_mul_f32 v[80:81], v[80:81], v[72:73]
	v_cvt_pk_bf16_f32 v136, v136, v137
	v_cvt_pk_bf16_f32 v137, v138, v139
	v_cvt_pk_bf16_f32 v138, v78, v79
	v_cvt_pk_bf16_f32 v139, v80, v81
	s_nop 1
	v_permlane32_swap_b32 v136, v138
	v_permlane32_swap_b32 v137, v139
	s_nop 0
	global_store_dwordx4 v[132:133], v[136:139], off
	s_waitcnt vmcnt(13)
	v_pk_mul_f32 v[66:67], v[20:21], v[66:67] op_sel_hi:[0,1]
	v_pk_mul_f32 v[68:69], v[20:21], v[68:69] op_sel_hi:[0,1]
	v_pk_mul_f32 v[62:63], v[20:21], v[62:63] op_sel_hi:[0,1]
	v_pk_mul_f32 v[64:65], v[20:21], v[64:65] op_sel_hi:[0,1]
	v_pk_mul_f32 v[82:83], v[82:83], v[66:67]
	v_pk_mul_f32 v[84:85], v[84:85], v[68:69]
	v_pk_mul_f32 v[86:87], v[86:87], v[62:63]
	v_pk_mul_f32 v[88:89], v[88:89], v[64:65]
	v_cvt_pk_bf16_f32 v82, v82, v83
	v_cvt_pk_bf16_f32 v83, v84, v85
	v_cvt_pk_bf16_f32 v84, v86, v87
	v_cvt_pk_bf16_f32 v85, v88, v89
	s_nop 1
	v_permlane32_swap_b32 v82, v84
	v_permlane32_swap_b32 v83, v85
	s_nop 0
	global_store_dwordx4 v[132:133], v[82:85], off offset:32
	s_waitcnt vmcnt(12)
; __device__ __forceinline__ unsigned cvt_pk_bf16(float lo, float hi) { f32x2 v = {lo, hi}; bf16x2_t b = __builtin_convertvector(v, bf16x2_t); return __builtin_bit_cast(unsigned, b); }
; __global__ void __launch_bounds__(512, 2) mega_fwd(Args a) {
;     ...
;                 bf16_t* op = OA + row * 1024 + h * 128;
; #pragma unroll
;                 for (int d = 0; d < 4; ++d)
; #pragma unroll
;                     for (int g4 = 0; g4 < 4; ++g4) { const int dd = 32 * d + 8 * g4 + 4 * hi; const f32x4 gs = *(const f32x4*)(a.in[10] + dd);
;                         u32x2 w; w.x = cvt_pk_bf16(o[d][4 * g4 + 0] * rinv * gs[0], o[d][4 * g4 + 1] * rinv * gs[1]); w.y = cvt_pk_bf16(o[d][4 * g4 + 2] * rinv * gs[2], o[d][4 * g4 + 3] * rinv * gs[3]);
;                         *(u32x2*)(op + dd) = w; }
	v_pk_mul_f32 v[58:59], v[20:21], v[58:59] op_sel_hi:[0,1]
	v_pk_mul_f32 v[60:61], v[20:21], v[60:61] op_sel_hi:[0,1]
	v_pk_mul_f32 v[54:55], v[20:21], v[54:55] op_sel_hi:[0,1]
	v_pk_mul_f32 v[56:57], v[20:21], v[56:57] op_sel_hi:[0,1]
	v_pk_mul_f32 v[90:91], v[90:91], v[58:59]
	v_pk_mul_f32 v[92:93], v[92:93], v[60:61]
	v_pk_mul_f32 v[94:95], v[94:95], v[54:55]
	v_pk_mul_f32 v[96:97], v[96:97], v[56:57]
	v_cvt_pk_bf16_f32 v90, v90, v91
	v_cvt_pk_bf16_f32 v91, v92, v93
	v_cvt_pk_bf16_f32 v92, v94, v95
	v_cvt_pk_bf16_f32 v93, v96, v97
	s_nop 1
	v_permlane32_swap_b32 v90, v92
	v_permlane32_swap_b32 v91, v93
	s_nop 0
	global_store_dwordx4 v[132:133], v[90:93], off offset:64
	s_waitcnt vmcnt(11)
	v_pk_mul_f32 v[48:49], v[20:21], v[48:49] op_sel_hi:[0,1]
	v_pk_mul_f32 v[46:47], v[20:21], v[46:47] op_sel_hi:[0,1]
	v_pk_mul_f32 v[42:43], v[20:21], v[42:43] op_sel_hi:[0,1]
	v_pk_mul_f32 v[44:45], v[20:21], v[44:45] op_sel_hi:[0,1]
	v_pk_mul_f32 v[98:99], v[98:99], v[48:49]
	v_pk_mul_f32 v[100:101], v[100:101], v[46:47]
	v_pk_mul_f32 v[102:103], v[102:103], v[42:43]
	v_pk_mul_f32 v[104:105], v[104:105], v[44:45]
	v_cvt_pk_bf16_f32 v98, v98, v99
	v_cvt_pk_bf16_f32 v99, v100, v101
	v_cvt_pk_bf16_f32 v100, v102, v103
	v_cvt_pk_bf16_f32 v101, v104, v105
	s_nop 1
	v_permlane32_swap_b32 v98, v100
	v_permlane32_swap_b32 v99, v101
	s_nop 0
	global_store_dwordx4 v[132:133], v[98:101], off offset:96
	s_waitcnt vmcnt(10)
	v_pk_mul_f32 v[38:39], v[20:21], v[38:39] op_sel_hi:[0,1]
	v_pk_mul_f32 v[40:41], v[20:21], v[40:41] op_sel_hi:[0,1]
	v_pk_mul_f32 v[32:33], v[20:21], v[32:33] op_sel_hi:[0,1]
	v_pk_mul_f32 v[30:31], v[20:21], v[30:31] op_sel_hi:[0,1]
	v_pk_mul_f32 v[106:107], v[106:107], v[38:39]
	v_pk_mul_f32 v[108:109], v[108:109], v[40:41]
	v_pk_mul_f32 v[110:111], v[110:111], v[32:33]
	v_pk_mul_f32 v[112:113], v[112:113], v[30:31]
	v_cvt_pk_bf16_f32 v106, v106, v107
	v_cvt_pk_bf16_f32 v107, v108, v109
	v_cvt_pk_bf16_f32 v108, v110, v111
	v_cvt_pk_bf16_f32 v109, v112, v113
	s_nop 1
	v_permlane32_swap_b32 v106, v108
	v_permlane32_swap_b32 v107, v109
	s_nop 0
	global_store_dwordx4 v[132:133], v[106:109], off offset:128
	s_waitcnt vmcnt(9)
	v_pk_mul_f32 v[26:27], v[20:21], v[26:27] op_sel_hi:[0,1]
	v_pk_mul_f32 v[28:29], v[20:21], v[28:29] op_sel_hi:[0,1]
	v_pk_mul_f32 v[22:23], v[20:21], v[22:23] op_sel_hi:[0,1]
	v_pk_mul_f32 v[24:25], v[20:21], v[24:25] op_sel_hi:[0,1]
	v_pk_mul_f32 v[114:115], v[114:115], v[26:27]
	v_pk_mul_f32 v[116:117], v[116:117], v[28:29]
	v_pk_mul_f32 v[118:119], v[118:119], v[22:23]
	v_pk_mul_f32 v[120:121], v[120:121], v[24:25]
	v_cvt_pk_bf16_f32 v114, v114, v115
	v_cvt_pk_bf16_f32 v115, v116, v117
	v_cvt_pk_bf16_f32 v116, v118, v119
	v_cvt_pk_bf16_f32 v117, v120, v121
	s_nop 1
	v_permlane32_swap_b32 v114, v116
	v_permlane32_swap_b32 v115, v117
	s_nop 0
	global_store_dwordx4 v[132:133], v[114:117], off offset:160
	s_waitcnt vmcnt(8)
	v_pk_mul_f32 v[16:17], v[20:21], v[16:17] op_sel_hi:[0,1]
	v_pk_mul_f32 v[12:13], v[20:21], v[12:13] op_sel_hi:[0,1]
	v_pk_mul_f32 v[6:7], v[20:21], v[6:7] op_sel_hi:[0,1]
	v_pk_mul_f32 v[8:9], v[20:21], v[8:9] op_sel_hi:[0,1]
	v_pk_mul_f32 v[122:123], v[122:123], v[16:17]
	v_pk_mul_f32 v[124:125], v[124:125], v[12:13]
	v_pk_mul_f32 v[140:141], v[140:141], v[6:7]
	v_pk_mul_f32 v[142:143], v[142:143], v[8:9]
	v_cvt_pk_bf16_f32 v122, v122, v123
	v_cvt_pk_bf16_f32 v123, v124, v125
	v_cvt_pk_bf16_f32 v124, v140, v141
	v_cvt_pk_bf16_f32 v125, v142, v143
	s_nop 1
	v_permlane32_swap_b32 v122, v124
	v_permlane32_swap_b32 v123, v125
	s_nop 0
	global_store_dwordx4 v[132:133], v[122:125], off offset:192
	s_waitcnt vmcnt(7)
	v_pk_mul_f32 v[2:3], v[20:21], v[2:3] op_sel_hi:[0,1]
	v_pk_mul_f32 v[4:5], v[20:21], v[4:5] op_sel_hi:[0,1]
	v_pk_mul_f32 v[14:15], v[20:21], v[14:15] op_sel_hi:[0,1]
	v_pk_mul_f32 v[10:11], v[20:21], v[10:11] op_sel_hi:[0,1]
	v_pk_mul_f32 v[144:145], v[144:145], v[2:3]
	v_pk_mul_f32 v[146:147], v[146:147], v[4:5]
	v_pk_mul_f32 v[150:151], v[150:151], v[14:15]
	v_pk_mul_f32 v[152:153], v[152:153], v[10:11]
	v_cvt_pk_bf16_f32 v144, v144, v145
	v_cvt_pk_bf16_f32 v145, v146, v147
	v_cvt_pk_bf16_f32 v146, v150, v151
	v_cvt_pk_bf16_f32 v147, v152, v153
	s_nop 1
	v_permlane32_swap_b32 v144, v146
	v_permlane32_swap_b32 v145, v147
	s_nop 0
	global_store_dwordx4 v[132:133], v[144:147], off offset:224

; __device__ __forceinline__ unsigned cvt_pk_bf16(float lo, float hi) { f32x2 v = {lo, hi}; bf16x2_t b = __builtin_convertvector(v, bf16x2_t); return __builtin_bit_cast(unsigned, b); }
; template <int DH, bool MOBA>
; __device__ __forceinline__ void flash_pass(LAS unsigned char* lds, const bf16_t* qrow, const bf16_t* kbase, const bf16_t* vtbase, int q0, int qblk, float sl2, unsigned sel, f32x16 (&o)[4], int tid) {
;     ...
;     const float lt = l_run + __shfl_xor(l_run, 32), inv = 1.0f / lt;
; #pragma unroll
;     for (int d = 0; d < 4; ++d)
; #pragma unroll
;         for (int r = 0; r < 16; ++r) o[d][r] *= inv;
; __global__ void __launch_bounds__(512, 2) mega_fwd(Args a) {
;     ...
;                 bf16_t* op = OB + row * 1024 + h * 128;
; #pragma unroll
;                 for (int d = 0; d < 4; ++d)
; #pragma unroll
;                     for (int g4 = 0; g4 < 4; ++g4) { const int dd = 32 * d + 8 * g4 + 4 * hi;
;                         u32x2 w; w.x = cvt_pk_bf16(o[d][4 * g4 + 0], o[d][4 * g4 + 1]); w.y = cvt_pk_bf16(o[d][4 * g4 + 2], o[d][4 * g4 + 3]);
;                         *(u32x2*)(op + dd) = w; }
.LBB0_685:
	ds_bpermute_b32 v1, v223, v202
	v_mov_b32_e32 v155, v0
	s_waitcnt lgkmcnt(0)
	v_add_f32_e32 v1, v202, v1
	v_div_scale_f32 v2, s[0:1], v1, v1, 1.0
	v_rcp_f32_e32 v3, v2
	v_div_scale_f32 v4, vcc, 1.0, v1, 1.0
	s_mov_b64 s[0:1], 0
	v_fma_f32 v5, -v2, v3, 1.0
	v_fmac_f32_e32 v3, v5, v3
	v_mul_f32_e32 v5, v4, v3
	v_fma_f32 v6, -v2, v5, v4
	v_fmac_f32_e32 v5, v6, v3
	v_fma_f32 v2, -v2, v5, v4
	v_div_fmas_f32 v2, v2, v3, v5
	v_div_fixup_f32 v2, v2, v1, 1.0
	v_pk_mul_f32 v[4:5], v[64:65], v[2:3] op_sel_hi:[1,0]
	v_pk_mul_f32 v[6:7], v[66:67], v[2:3] op_sel_hi:[1,0]
	v_pk_mul_f32 v[8:9], v[68:69], v[2:3] op_sel_hi:[1,0]
	v_pk_mul_f32 v[10:11], v[70:71], v[2:3] op_sel_hi:[1,0]
	v_pk_mul_f32 v[12:13], v[72:73], v[2:3] op_sel_hi:[1,0]
	v_pk_mul_f32 v[14:15], v[74:75], v[2:3] op_sel_hi:[1,0]
	v_pk_mul_f32 v[64:65], v[76:77], v[2:3] op_sel_hi:[1,0]
	v_pk_mul_f32 v[66:67], v[78:79], v[2:3] op_sel_hi:[1,0]
	v_pk_mul_f32 v[48:49], v[48:49], v[2:3] op_sel_hi:[1,0]
	v_pk_mul_f32 v[50:51], v[50:51], v[2:3] op_sel_hi:[1,0]
	v_pk_mul_f32 v[52:53], v[52:53], v[2:3] op_sel_hi:[1,0]
	v_pk_mul_f32 v[54:55], v[54:55], v[2:3] op_sel_hi:[1,0]
	v_pk_mul_f32 v[56:57], v[56:57], v[2:3] op_sel_hi:[1,0]
	v_pk_mul_f32 v[58:59], v[58:59], v[2:3] op_sel_hi:[1,0]
	v_pk_mul_f32 v[60:61], v[60:61], v[2:3] op_sel_hi:[1,0]
	v_pk_mul_f32 v[62:63], v[62:63], v[2:3] op_sel_hi:[1,0]
	v_pk_mul_f32 v[32:33], v[32:33], v[2:3] op_sel_hi:[1,0]
	v_pk_mul_f32 v[34:35], v[34:35], v[2:3] op_sel_hi:[1,0]
	v_pk_mul_f32 v[36:37], v[36:37], v[2:3] op_sel_hi:[1,0]
	v_pk_mul_f32 v[38:39], v[38:39], v[2:3] op_sel_hi:[1,0]
	v_pk_mul_f32 v[40:41], v[40:41], v[2:3] op_sel_hi:[1,0]
	v_pk_mul_f32 v[42:43], v[42:43], v[2:3] op_sel_hi:[1,0]
	v_pk_mul_f32 v[44:45], v[44:45], v[2:3] op_sel_hi:[1,0]
	v_pk_mul_f32 v[46:47], v[46:47], v[2:3] op_sel_hi:[1,0]
	v_pk_mul_f32 v[16:17], v[16:17], v[2:3] op_sel_hi:[1,0]
	v_pk_mul_f32 v[18:19], v[18:19], v[2:3] op_sel_hi:[1,0]
	v_pk_mul_f32 v[20:21], v[20:21], v[2:3] op_sel_hi:[1,0]
	v_pk_mul_f32 v[22:23], v[22:23], v[2:3] op_sel_hi:[1,0]
	v_pk_mul_f32 v[24:25], v[24:25], v[2:3] op_sel_hi:[1,0]
	v_pk_mul_f32 v[26:27], v[26:27], v[2:3] op_sel_hi:[1,0]
	v_pk_mul_f32 v[28:29], v[28:29], v[2:3] op_sel_hi:[1,0]
	v_pk_mul_f32 v[2:3], v[30:31], v[2:3] op_sel_hi:[1,0]
	v_lshlrev_b64 v[30:31], 11, v[152:153]
	v_lshl_add_u64 v[30:31], s[8:9], 0, v[30:31]
	v_lshl_add_u64 v[30:31], v[30:31], 0, s[10:11]
	v_cvt_pk_bf16_f32 v4, v4, v5
	v_cvt_pk_bf16_f32 v5, v6, v7
	v_cvt_pk_bf16_f32 v6, v8, v9
	v_cvt_pk_bf16_f32 v7, v10, v11
	v_lshl_add_u64 v[8:9], v[30:31], 0, v[154:155]
	v_mbcnt_lo_u32_b32 v10, -1, 0
	v_mbcnt_hi_u32_b32 v10, -1, v10
	v_lshrrev_b32_e32 v10, 5, v10
	v_lshlrev_b32_e32 v10, 3, v10
	v_mov_b32_e32 v11, 0
	v_lshl_add_u64 v[8:9], v[8:9], 0, v[10:11]
	v_permlane32_swap_b32 v4, v6
	v_permlane32_swap_b32 v5, v7
	s_nop 0
	global_store_dwordx4 v[8:9], v[4:7], off
	v_cvt_pk_bf16_f32 v12, v12, v13
	v_cvt_pk_bf16_f32 v13, v14, v15
	v_cvt_pk_bf16_f32 v14, v64, v65
	v_cvt_pk_bf16_f32 v15, v66, v67
	s_nop 1
	v_permlane32_swap_b32 v12, v14
	v_permlane32_swap_b32 v13, v15
	s_nop 0
	global_store_dwordx4 v[8:9], v[12:15], off offset:32
	v_cvt_pk_bf16_f32 v48, v48, v49
	v_cvt_pk_bf16_f32 v49, v50, v51
	v_cvt_pk_bf16_f32 v50, v52, v53
	v_cvt_pk_bf16_f32 v51, v54, v55
	s_nop 1
	v_permlane32_swap_b32 v48, v50
	v_permlane32_swap_b32 v49, v51
	s_nop 0
	global_store_dwordx4 v[8:9], v[48:51], off offset:64
	v_cvt_pk_bf16_f32 v56, v56, v57
	v_cvt_pk_bf16_f32 v57, v58, v59
	v_cvt_pk_bf16_f32 v58, v60, v61
	v_cvt_pk_bf16_f32 v59, v62, v63
	s_nop 1
	v_permlane32_swap_b32 v56, v58
	v_permlane32_swap_b32 v57, v59
	s_nop 0
	global_store_dwordx4 v[8:9], v[56:59], off offset:96
	v_cvt_pk_bf16_f32 v32, v32, v33
	v_cvt_pk_bf16_f32 v33, v34, v35
	v_cvt_pk_bf16_f32 v34, v36, v37
	v_cvt_pk_bf16_f32 v35, v38, v39
	s_nop 1
	v_permlane32_swap_b32 v32, v34
	v_permlane32_swap_b32 v33, v35
	s_nop 0
	global_store_dwordx4 v[8:9], v[32:35], off offset:128
	v_cvt_pk_bf16_f32 v40, v40, v41
	v_cvt_pk_bf16_f32 v41, v42, v43
	v_cvt_pk_bf16_f32 v42, v44, v45
	v_cvt_pk_bf16_f32 v43, v46, v47
	s_nop 1
	v_permlane32_swap_b32 v40, v42
	v_permlane32_swap_b32 v41, v43
	s_nop 0
	global_store_dwordx4 v[8:9], v[40:43], off offset:160
	v_cvt_pk_bf16_f32 v16, v16, v17
	v_cvt_pk_bf16_f32 v17, v18, v19
	v_cvt_pk_bf16_f32 v18, v20, v21
	v_cvt_pk_bf16_f32 v19, v22, v23
	s_nop 1
	v_permlane32_swap_b32 v16, v18
	v_permlane32_swap_b32 v17, v19
	s_nop 0
	global_store_dwordx4 v[8:9], v[16:19], off offset:192
	v_cvt_pk_bf16_f32 v24, v24, v25
	v_cvt_pk_bf16_f32 v25, v26, v27
	v_cvt_pk_bf16_f32 v26, v28, v29
	v_cvt_pk_bf16_f32 v27, v2, v3
	s_nop 1
	v_permlane32_swap_b32 v24, v26
	v_permlane32_swap_b32 v25, v27
	s_nop 0
	global_store_dwordx4 v[8:9], v[24:27], off offset:224
